# pipelined unit entry: kmax retired by the hand-over wait, prologue kmax wait skipped on that path
# baseline (speedup 1.0000x reference)
.LBB0_297:
	s_cmpk_gt_i32 s46, 0x4f
	v_readlane_b32 s4, v245, 14
	s_cselect_b64 s[2:3], -1, 0
	s_cmp_lt_u32 s46, s4
	s_cselect_b64 s[4:5], -1, 0
	s_and_b64 s[2:3], s[2:3], s[4:5]
	s_andn2_b64 vcc, exec, s[2:3]
	s_mov_b64 s[2:3], -1
	s_cbranch_vccz .LBB0_352
	s_cmpk_gt_i32 s46, 0x4f
	v_readlane_b32 s2, v245, 13
	s_cselect_b32 s2, s2, 0
	s_sub_i32 s2, s46, s2
	s_bfe_u32 s4, s2, 0x30001
	s_and_b32 s3, s2, 1
	s_xor_b32 s5, s4, 7
	s_or_b32 s4, s4, 8
	s_cmp_eq_u32 s3, 0
	s_cselect_b32 s3, s4, s5
	s_mov_b64 s[4:5], s[0:1]
	s_mov_b64 s[12:13], s[0:1]
	s_load_dwordx2 s[4:5], s[4:5], 0x80
	s_load_dwordx2 s[74:75], s[12:13], 0x80
	s_mov_b64 s[12:13], s[0:1]
	s_ashr_i32 s2, s2, 4
	s_load_dwordx2 s[78:79], s[12:13], 0x28
	s_sub_i32 s12, 8, s2
	v_cvt_f32_i32_e32 v0, s12
	v_mov_b32_e32 v19, v220
	v_readlane_b32 s13, v245, 17
	v_exp_f32_e64 v0, -v0
	s_sub_i32 s55, 7, s2
	s_lshl_b32 s76, s55, 6
	v_ashrrev_i32_e32 v2, 5, v19
	v_readfirstlane_b32 s12, v0
	v_ashrrev_i32_e32 v0, 3, v19
	v_add_u32_e32 v0, s13, v0
	v_mul_lo_u32 v3, v0, s88
	v_lshrrev_b32_e32 v0, 1, v0
	s_add_i32 s13, s76, 0x200
	v_xor_b32_e32 v0, v0, v19
	v_add_u32_e32 v3, s13, v3
	v_lshlrev_b32_e32 v0, 3, v0
	v_readlane_b32 s13, v245, 16
	v_and_or_b32 v0, v0, 56, v3
	v_lshlrev_b32_e32 v4, 3, v19
	v_lshl_add_u32 v3, v2, 3, s13
	v_readlane_b32 s13, v245, 18
	s_add_i32 s13, s13, s76
	v_and_b32_e32 v20, 24, v4
	v_or_b32_e32 v9, s13, v20
	v_readlane_b32 s13, v245, 19
	s_waitcnt lgkmcnt(0)
	s_add_u32 s4, s4, s13
	s_addc_u32 s5, s5, 0
	s_add_u32 s60, s4, 0x13200000
	s_addc_u32 s61, s5, 0
	s_mul_i32 s4, s3, 0xc0000
	s_add_u32 s80, s60, s4
	v_lshlrev_b32_e32 v0, 1, v0
	s_addc_u32 s81, s61, 0
	s_movk_i32 s4, 0xfc00
	v_lshl_add_u64 v[4:5], s[80:81], 0, v[0:1]
	s_mov_b32 s5, -1
	v_lshl_add_u64 v[6:7], v[4:5], 0, s[4:5]
	v_readlane_b32 s5, v245, 22
	s_mov_b32 s4, m0
	s_mov_b32 m0, s5
	s_nop 0
	global_load_lds_dwordx4 v[6:7], off
	s_mov_b32 m0, s4
	s_mov_b64 s[4:5], 0x2fc00
	v_bfe_u32 v8, v19, 2, 3
	v_lshl_add_u64 v[6:7], v[4:5], 0, s[4:5]
	v_readlane_b32 s5, v245, 20
	s_mov_b32 s4, m0
	s_mov_b32 m0, s5
	s_nop 0
	global_load_lds_dwordx4 v[6:7], off
	s_mov_b32 m0, s4
	s_mov_b64 s[4:5], 0x5fc00
	v_or_b32_e32 v3, v3, v8
	v_lshl_add_u64 v[6:7], v[4:5], 0, s[4:5]
	v_readlane_b32 s5, v245, 21
	s_mov_b32 s4, m0
	s_mov_b32 m0, s5
	s_nop 0
	global_load_lds_dwordx4 v[6:7], off
	s_mov_b32 m0, s4
	s_mov_b64 s[4:5], 0x8fc00
	v_mul_lo_u32 v3, v3, s88
	v_lshl_add_u64 v[6:7], v[4:5], 0, s[4:5]
	v_readlane_b32 s5, v245, 23
	s_mov_b32 s4, m0
	s_mov_b32 m0, s5
	s_nop 0
	global_load_lds_dwordx4 v[6:7], off
	s_mov_b32 m0, s4
	v_add_lshl_u32 v170, v9, v3, 1
	s_mov_b32 s4, m0
	s_mov_b32 m0, s64
	s_nop 0
	global_load_lds_dwordx4 v[4:5], off
	s_mov_b32 m0, s4
	v_mov_b32_e32 v171, v1
	v_lshl_add_u64 v[4:5], s[80:81], 0, v[170:171]
	v_readlane_b32 s5, v245, 24
	s_mov_b32 s4, m0
	s_mov_b32 m0, s5
	s_nop 0
	global_load_lds_dwordx4 v[4:5], off
	s_mov_b32 m0, s4
	v_lshlrev_b32_e32 v4, 2, v19
	v_readlane_b32 s4, v245, 25
	v_and_b32_e32 v9, 4, v4
	v_bitop3_b32 v4, v4, v8, 4 bitop3:0x6c
	v_lshl_add_u32 v3, v19, 6, s4
	v_and_b32_e32 v3, 0xffffff80, v3
	v_add_u32_e32 v3, s63, v3
	v_lshl_add_u32 v4, v4, 4, v3
	s_ashr_i32 s101, s2, 31
	s_mov_b32 s100, s2
	s_lshl_b64 s[100:101], s[100:101], 2
	s_sub_u32 s100, s7, s100
	s_subb_u32 s101, s33, s101
	v_mov_b32_e32 v248, 0
	global_load_dword v249, v248, s[100:101] offset:28 sc1
	s_add_u32 s100, s80, 0x30000
	s_addc_u32 s101, s81, 0
	v_lshl_add_u64 v[250:251], s[100:101], 0, v[0:1]
	v_lshl_add_u64 v[252:253], s[100:101], 0, v[170:171]
	v_readlane_b32 s98, v245, 27
	s_mov_b32 s99, m0
	s_mov_b32 m0, s98
	s_nop 0
	global_load_lds_dwordx4 v[250:251], off
	v_readlane_b32 s98, v245, 28
	s_nop 0
	s_mov_b32 m0, s98
	s_nop 0
	global_load_lds_dwordx4 v[252:253], off
	s_add_u32 s100, s80, 0x60000
	s_addc_u32 s101, s81, 0
	v_lshl_add_u64 v[250:251], s[100:101], 0, v[0:1]
	v_lshl_add_u64 v[252:253], s[100:101], 0, v[170:171]
	v_readlane_b32 s98, v245, 29
	s_nop 0
	s_mov_b32 m0, s98
	s_nop 0
	global_load_lds_dwordx4 v[250:251], off
	v_readlane_b32 s98, v245, 30
	s_nop 0
	s_mov_b32 m0, s98
	s_nop 0
	global_load_lds_dwordx4 v[252:253], off
	s_mov_b32 m0, s99
	s_mov_b32 s101, 0
	s_waitcnt vmcnt(5)

.LBB0_300:
	s_or_b64 exec, exec, s[4:5]
	s_lshl_b32 s4, s3, 8
	v_readlane_b32 s5, v245, 15
	s_lshl_b32 s69, s3, 2
	s_ashr_i32 s3, s2, 31
	s_add_i32 s68, s4, s5
	s_lshl_b64 s[2:3], s[2:3], 2
	s_sub_u32 s2, s7, s2
	v_mov_b32_e32 v3, s11
	v_mov_b32_e32 v8, s89
	s_subb_u32 s3, s33, s3
	v_mov_b32_e32 v175, 0
	s_waitcnt lgkmcnt(0)
	s_barrier
	ds_read_b128 v[4:7], v3
	ds_read_b128 v[8:11], v8
	v_and_b32_e32 v185, 31, v19
	v_lshrrev_b32_e32 v3, 1, v19
	v_lshlrev_b32_e32 v172, 2, v2
	v_lshlrev_b32_e32 v12, 7, v185
	v_bitop3_b32 v2, v3, v2, 7 bitop3:0x6c
	v_mul_f32_e32 v18, s12, v235
	v_lshl_add_u32 v186, v2, 4, v12
	v_or_b32_e32 v2, s68, v185
	v_cvt_f32_i32_e32 v3, v172
	v_mul_f32_e32 v173, 0x42800000, v18
	s_mov_b32 s56, 0x41600000
	v_cvt_f32_u32_e32 v2, v2
	v_div_scale_f32 v58, s[2:3], v173, v173, s56
	v_cvt_f32_u32_e32 v13, s4
	v_rcp_f32_e32 v60, v58
	s_waitcnt lgkmcnt(1)
	v_max_f32_e32 v5, v5, v5
	v_max_f32_e32 v4, v4, v4
	v_sub_f32_e32 v187, v3, v2
	v_max_f32_e32 v2, v4, v5
	v_max3_f32 v2, v2, v6, v7
	v_fma_f32 v3, -v58, v60, 1.0
	v_add_f32_e32 v176, v187, v13
	s_waitcnt lgkmcnt(0)
	v_max3_f32 v23, v2, v8, v9
	v_fmac_f32_e32 v60, v3, v60
	v_pk_add_f32 v[2:3], v[176:177], s[14:15] op_sel_hi:[0,1]
	v_max3_f32 v23, v23, v10, v11
	v_and_b32_e32 v24, 0x7fffffff, v2
	s_mov_b32 s2, 0xf800000
	v_and_b32_e32 v25, 0x7fffffff, v3
	v_pk_add_f32 v[12:13], v[176:177], s[22:23] op_sel_hi:[0,1]
	v_pk_add_f32 v[14:15], v[176:177], s[24:25] op_sel_hi:[0,1]
	v_pk_add_f32 v[16:17], v[176:177], s[26:27] op_sel_hi:[0,1]
	v_add_f32_e32 v26, 1.0, v176
	v_and_b32_e32 v11, 0x7fffffff, v13
	v_and_b32_e32 v10, 0x7fffffff, v12
	v_and_b32_e32 v13, 0x7fffffff, v15
	v_and_b32_e32 v12, 0x7fffffff, v14
	v_and_b32_e32 v15, 0x7fffffff, v17
	v_and_b32_e32 v14, 0x7fffffff, v16
	v_and_b32_e32 v22, 0x7fffffff, v176
	v_pk_mul_f32 v[16:17], v[14:15], v[18:19] op_sel_hi:[1,0] neg_lo:[0,1] neg_hi:[0,1]
	v_pk_add_f32 v[8:9], v[176:177], s[20:21] op_sel_hi:[0,1]
	v_and_b32_e32 v9, 0x7fffffff, v9
	v_and_b32_e32 v8, 0x7fffffff, v8
	v_readlane_b32 s55, v245, 28
	v_pk_add_f32 v[4:5], v[176:177], s[16:17] op_sel_hi:[0,1]
	v_pk_add_f32 v[6:7], v[176:177], s[18:19] op_sel_hi:[0,1]
	v_xor_b32_e32 v188, 32, v186
	v_and_b32_e32 v5, 0x7fffffff, v5
	v_and_b32_e32 v4, 0x7fffffff, v4
	v_and_b32_e32 v7, 0x7fffffff, v7
	v_and_b32_e32 v6, 0x7fffffff, v6
	v_add_u32_e32 v61, 0, v188
	v_add_u32_e32 v189, s52, v186
	v_add_u32_e32 v192, s52, v188
	v_div_scale_f32 v59, s[4:5], s56, v173, s56
	v_pk_add_f32 v[42:43], v[176:177], s[28:29] op_sel_hi:[0,1]
	v_pk_add_f32 v[44:45], v[176:177], s[30:31] op_sel_hi:[0,1]
	v_pk_add_f32 v[46:47], v[176:177], s[34:35] op_sel_hi:[0,1]
	v_pk_add_f32 v[48:49], v[176:177], s[36:37] op_sel_hi:[0,1]
	v_pk_add_f32 v[50:51], v[176:177], s[38:39] op_sel_hi:[0,1]
	v_pk_add_f32 v[52:53], v[176:177], s[40:41] op_sel_hi:[0,1]
	v_pk_add_f32 v[54:55], v[176:177], s[42:43] op_sel_hi:[0,1]
	v_pk_add_f32 v[56:57], v[176:177], s[44:45] op_sel_hi:[0,1]
	v_and_b32_e32 v57, 0x7fffffff, v57
	v_and_b32_e32 v56, 0x7fffffff, v56
	v_and_b32_e32 v55, 0x7fffffff, v55
	v_and_b32_e32 v54, 0x7fffffff, v54
	v_and_b32_e32 v53, 0x7fffffff, v53
	v_and_b32_e32 v52, 0x7fffffff, v52
	v_and_b32_e32 v51, 0x7fffffff, v51
	v_and_b32_e32 v50, 0x7fffffff, v50
	v_and_b32_e32 v49, 0x7fffffff, v49
	v_and_b32_e32 v48, 0x7fffffff, v48
	v_and_b32_e32 v47, 0x7fffffff, v47
	v_and_b32_e32 v46, 0x7fffffff, v46
	v_and_b32_e32 v45, 0x7fffffff, v45
	s_cmp_lg_u32 s101, 0
	s_cbranch_scc1 .Lpipe_kmax_ok
	s_waitcnt vmcnt(4)
.Lpipe_kmax_ok:
	v_mul_f32_e32 v2, v23, v249
	v_mul_f32_e32 v3, 0x4f800000, v2
	v_cmp_gt_f32_e32 vcc, s2, v2
	v_and_b32_e32 v23, 0x7fffffff, v26
	v_and_b32_e32 v44, 0x7fffffff, v44
	v_cndmask_b32_e32 v21, v2, v3, vcc
	v_sqrt_f32_e32 v27, v21
	v_pk_mul_f32 v[2:3], v[22:23], v[18:19] op_sel_hi:[1,0] neg_lo:[0,1] neg_hi:[0,1]
	v_and_b32_e32 v43, 0x7fffffff, v43
	v_and_b32_e32 v42, 0x7fffffff, v42
	v_add_u32_e32 v14, -1, v27
	v_add_u32_e32 v15, 1, v27
	v_fma_f32 v22, -v14, v27, v21
	v_fma_f32 v23, -v15, v27, v21
	v_cmp_ge_f32_e64 s[2:3], 0, v22
	v_pk_mul_f32 v[96:97], v[42:43], v[18:19] op_sel_hi:[1,0] neg_lo:[0,1] neg_hi:[0,1]
	v_pk_mul_f32 v[94:95], v[44:45], v[18:19] op_sel_hi:[1,0] neg_lo:[0,1] neg_hi:[0,1]
	v_cndmask_b32_e64 v14, v27, v14, s[2:3]
	v_cmp_lt_f32_e64 s[2:3], 0, v23
	v_pk_mul_f32 v[92:93], v[46:47], v[18:19] op_sel_hi:[1,0] neg_lo:[0,1] neg_hi:[0,1]
	v_pk_mul_f32 v[90:91], v[48:49], v[18:19] op_sel_hi:[1,0] neg_lo:[0,1] neg_hi:[0,1]
	v_cndmask_b32_e64 v14, v14, v15, s[2:3]
	v_mul_f32_e32 v15, 0x37800000, v14
	v_cndmask_b32_e32 v14, v14, v15, vcc
	v_cmp_class_f32_e32 vcc, v21, v232
	v_pk_mul_f32 v[88:89], v[50:51], v[18:19] op_sel_hi:[1,0] neg_lo:[0,1] neg_hi:[0,1]
	v_pk_mul_f32 v[86:87], v[52:53], v[18:19] op_sel_hi:[1,0] neg_lo:[0,1] neg_hi:[0,1]
	v_cndmask_b32_e32 v14, v14, v21, vcc
	v_mul_f32_e32 v21, 0x3f828f5c, v14
	v_add_f32_e32 v246, 0x42000000, v21
	s_nop 0
	v_readfirstlane_b32 s98, v246
	v_fmaak_f32 v22, 2.0, v21, 0x42000000
	v_div_scale_f32 v23, s[2:3], v18, v18, v22
	v_rcp_f32_e32 v26, v23
	v_pk_mul_f32 v[14:15], v[12:13], v[18:19] op_sel_hi:[1,0] neg_lo:[0,1] neg_hi:[0,1]
	v_div_scale_f32 v12, vcc, v22, v18, v22
	v_fma_f32 v13, -v23, v26, 1.0
	v_fmac_f32_e32 v26, v13, v26
	v_mul_f32_e32 v13, v12, v26
	v_fma_f32 v27, -v23, v13, v12
	v_fmac_f32_e32 v13, v27, v26
	v_fma_f32 v12, -v23, v13, v12
	v_div_fmas_f32 v12, v12, v26, v13
	v_div_fixup_f32 v22, v12, v18, v22
	v_cvt_i32_f32_e32 v23, v22
	v_cmp_gt_f32_e32 vcc, s90, v22
	v_pk_mul_f32 v[12:13], v[10:11], v[18:19] op_sel_hi:[1,0] neg_lo:[0,1] neg_hi:[0,1]
	v_pk_mul_f32 v[10:11], v[8:9], v[18:19] op_sel_hi:[1,0] neg_lo:[0,1] neg_hi:[0,1]
	v_readfirstlane_b32 s2, v23
	s_add_i32 s12, s2, 1
	s_and_b64 s[2:3], vcc, exec
	s_cselect_b32 s2, s12, 0x2000
	s_add_i32 s12, s2, 62
	s_add_i32 s2, s2, -2
	s_ashr_i32 s12, s12, 6
	s_ashr_i32 s2, s2, 6
	s_xor_b32 s3, s69, 60
	s_min_i32 s77, s69, s12
	s_add_i32 s2, s2, 1
	s_min_i32 s2, s3, s2
	s_add_i32 s82, s77, 4
	s_add_u32 s12, s80, 0x30000
	s_addc_u32 s13, s81, 0
	s_add_u32 s12, s80, 0x60000
	v_readlane_b32 s13, v245, 27
	s_addc_u32 s13, s81, 0
	v_add_u32_e32 v26, 0, v186
	v_readlane_b32 s12, v245, 29
	v_readlane_b32 s12, v245, 30
	v_pk_mul_f32 v[8:9], v[6:7], v[18:19] op_sel_hi:[1,0] neg_lo:[0,1] neg_hi:[0,1]
	v_pk_mul_f32 v[6:7], v[4:5], v[18:19] op_sel_hi:[1,0] neg_lo:[0,1] neg_hi:[0,1]
	v_pk_mul_f32 v[4:5], v[24:25], v[18:19] op_sel_hi:[1,0] neg_lo:[0,1] neg_hi:[0,1]
	ds_read_b128 v[22:25], v26
	ds_read_b128 v[26:29], v26 offset:4096
	ds_read_b128 v[30:33], v61
	ds_read_b128 v[34:37], v189
	ds_read_b128 v[38:41], v192
	s_waitcnt lgkmcnt(1)
	v_mfma_f32_32x32x16_bf16 v[98:113], v[22:25], v[34:37], v[2:17]
	v_mul_f32_e32 v22, v59, v60
	v_fma_f32 v23, -v58, v22, v59
	v_fmac_f32_e32 v22, v23, v60
	v_mul_f32_e64 v84, v54, -v18
	v_mul_f32_e64 v85, v55, -v18
	v_pk_mul_f32 v[82:83], v[56:57], v[18:19] op_sel_hi:[1,0] neg_lo:[0,1] neg_hi:[0,1]
	v_fma_f32 v23, -v58, v22, v59
	s_mov_b64 vcc, s[4:5]
	v_mfma_f32_32x32x16_bf16 v[82:97], v[26:29], v[34:37], v[82:97]
	v_div_fmas_f32 v26, v23, v60, v22
	ds_read_b128 v[22:25], v61 offset:4096
	v_div_fixup_f32 v26, v26, v173, s56
	v_cmp_gt_f32_e32 vcc, s24, v21
	s_add_i32 s83, s82, s2
	s_cmp_lt_i32 s83, 1
	v_cndmask_b32_e32 v21, 0, v26, vcc
	s_waitcnt lgkmcnt(1)
	v_mfma_f32_32x32x16_bf16 v[98:113], v[30:33], v[38:41], v[98:113]
	v_min_f32_e32 v21, 0x42800000, v21
	s_nop 0
	v_readfirstlane_b32 s3, v21
	s_waitcnt lgkmcnt(0)
	v_mfma_f32_32x32x16_bf16 v[82:97], v[22:25], v[38:41], v[82:97]
	s_cbranch_scc1 .LBB0_350
	v_lshrrev_b32_e32 v21, 2, v19
	v_lshlrev_b32_e32 v19, 1, v19
	v_cvt_i32_f32_e32 v193, s3
	v_and_or_b32 v21, v21, 3, v172
	v_and_or_b32 v19, v19, 32, v20
	v_readfirstlane_b32 s99, v193
	v_lshl_or_b32 v19, v21, 6, v19
	v_mov_b32_e32 v50, v1
	v_mov_b32_e32 v51, v1
	v_mov_b32_e32 v64, v1
	v_mov_b32_e32 v65, v1
	v_xor_b32_e32 v178, 0x80000000, v18
	v_add_u32_e32 v195, 0x2000, v19
	v_mul_f32_e32 v196, 0x42000000, v18
	v_mul_f32_e32 v197, 0xc2000000, v18
	s_add_i32 s86, s2, s77
	v_mov_b32_e32 v52, v1
	v_mov_b32_e32 v53, v1
	v_mov_b32_e32 v54, v1
	v_mov_b32_e32 v55, v1
	v_mov_b32_e32 v56, v1
	v_mov_b32_e32 v57, v1
	v_mov_b32_e32 v58, v1
	v_mov_b32_e32 v59, v1
	v_mov_b32_e32 v60, v1
	v_mov_b32_e32 v61, v1
	v_mov_b32_e32 v62, v1
	v_mov_b32_e32 v63, v1
	v_mov_b64_e32 v[18:19], v[50:51]
	v_mov_b64_e32 v[80:81], v[64:65]
	v_mov_b64_e32 v[34:35], v[50:51]
	v_mov_b32_e32 v180, v178
	v_mov_b32_e32 v181, v178
	v_xor_b32_e32 v194, 64, v186
	s_sub_i32 s84, s69, s77
	s_or_b32 s85, s69, 3
	v_xor_b32_e32 v198, 0x60, v186
	s_add_i32 s86, s86, 4
	s_add_i32 s87, s77, 3
	s_mov_b32 s88, 0
	v_mov_b32_e32 v174, v1
	v_mov_b32_e32 v175, v1
	v_mov_b32_e32 v182, 0
	s_mov_b32 s89, s69
	v_mov_b64_e32 v[20:21], v[52:53]
	v_mov_b64_e32 v[22:23], v[54:55]
	v_mov_b64_e32 v[24:25], v[56:57]
	v_mov_b64_e32 v[26:27], v[58:59]
	v_mov_b64_e32 v[28:29], v[60:61]
	v_mov_b64_e32 v[30:31], v[62:63]
	v_mov_b64_e32 v[32:33], v[64:65]
	v_mov_b64_e32 v[78:79], v[62:63]
	v_mov_b64_e32 v[76:77], v[60:61]
	v_mov_b64_e32 v[74:75], v[58:59]
	v_mov_b64_e32 v[72:73], v[56:57]
	v_mov_b64_e32 v[70:71], v[54:55]
	v_mov_b64_e32 v[68:69], v[52:53]
	v_mov_b64_e32 v[66:67], v[50:51]
	v_mov_b64_e32 v[36:37], v[52:53]
	v_mov_b64_e32 v[38:39], v[54:55]
	v_mov_b64_e32 v[40:41], v[56:57]
	v_mov_b64_e32 v[42:43], v[58:59]
	v_mov_b64_e32 v[44:45], v[60:61]
	v_mov_b64_e32 v[46:47], v[62:63]
	v_mov_b64_e32 v[48:49], v[64:65]
	v_add_u32_e32 v254, s52, v194
	v_add_u32_e32 v255, s52, v198
	v_add_u32_e32 v114, s88, v194
	ds_read_b128 v[158:161], v114
	ds_read_b128 v[150:153], v114 offset:4096
	v_add_u32_e32 v114, s88, v198
	ds_read_b128 v[154:157], v114
	ds_read_b128 v[146:149], v114 offset:4096
	ds_read_b128 v[166:169], v254
	ds_read_b128 v[162:165], v255
	s_mov_b32 s90, 0
	s_add_i32 s2, s90, 2
	s_cmp_ge_i32 s2, s83
	s_mov_b64 s[2:3], -1
	s_cbranch_scc0 .LBB0_303

.Lpipe_nofetch:
	s_add_u32 s2, s78, s8
	s_addc_u32 s3, s79, s9
	v_ashrrev_i32_e32 v173, 31, v172
	v_lshl_add_u64 v[2:3], v[172:173], 2, s[2:3]
	v_mov_b32_e32 v0, v175
	global_load_dwordx4 v[94:97], v[2:3], off
	global_load_dwordx4 v[90:93], v[2:3], off offset:32
	global_load_dwordx4 v[86:89], v[2:3], off offset:64
	global_load_dwordx4 v[82:85], v[2:3], off offset:96
	global_load_dwordx4 v[14:17], v[2:3], off offset:128
	global_load_dwordx4 v[10:13], v[2:3], off offset:160
	global_load_dwordx4 v[6:9], v[2:3], off offset:192
	s_nop 0
	global_load_dwordx4 v[2:5], v[2:3], off offset:224
	v_mov_b32_e32 v147, 0
	s_cmpk_gt_i32 s46, 0x4f
	v_readlane_b32 s2, v245, 13
	s_cselect_b32 s2, s2, 0
	s_sub_i32 s2, s46, s2
	s_bfe_u32 s4, s2, 0x30001
	s_and_b32 s3, s2, 1
	s_xor_b32 s5, s4, 7
	s_or_b32 s4, s4, 8
	s_cmp_eq_u32 s3, 0
	s_cselect_b32 s3, s4, s5
	s_mov_b64 s[4:5], s[0:1]
	s_mov_b64 s[12:13], s[0:1]
	s_load_dwordx2 s[4:5], s[4:5], 0x80
	s_mov_b64 s[12:13], s[0:1]
	s_ashr_i32 s2, s2, 4
	s_sub_i32 s12, 8, s2
	v_cvt_f32_i32_e32 v146, s12
	v_mov_b32_e32 v156, v220
	v_readlane_b32 s13, v245, 17
	v_exp_f32_e64 v146, -v146
	s_sub_i32 s55, 7, s2
	s_lshl_b32 s55, s55, 6
	v_ashrrev_i32_e32 v148, 5, v156
	v_readfirstlane_b32 s12, v146
	v_ashrrev_i32_e32 v146, 3, v156
	v_add_u32_e32 v146, s13, v146
	v_mul_lo_u32 v149, v146, s88
	v_lshrrev_b32_e32 v146, 1, v146
	s_add_i32 s13, s55, 0x200
	v_xor_b32_e32 v146, v146, v156
	v_add_u32_e32 v149, s13, v149
	v_lshlrev_b32_e32 v146, 3, v146
	v_readlane_b32 s13, v245, 16
	v_and_or_b32 v146, v146, 56, v149
	v_lshlrev_b32_e32 v150, 3, v156
	v_lshl_add_u32 v149, v148, 3, s13
	v_readlane_b32 s13, v245, 18
	s_add_i32 s13, s13, s55
	v_and_b32_e32 v157, 24, v150
	v_or_b32_e32 v155, s13, v157
	v_readlane_b32 s13, v245, 19
	s_waitcnt lgkmcnt(0)
	s_add_u32 s4, s4, s13
	s_addc_u32 s5, s5, 0
	s_add_u32 s60, s4, 0x13200000
	s_addc_u32 s61, s5, 0
	s_mul_i32 s4, s3, 0xc0000
	s_add_u32 s80, s60, s4
	v_lshlrev_b32_e32 v146, 1, v146
	s_addc_u32 s81, s61, 0
	s_movk_i32 s4, 0xfc00
	v_lshl_add_u64 v[150:151], s[80:81], 0, v[146:147]
	s_mov_b32 s5, -1
	v_lshl_add_u64 v[152:153], v[150:151], 0, s[4:5]
	v_readlane_b32 s5, v245, 22
	s_mov_b32 s4, m0
	s_mov_b32 m0, s5
	s_nop 0
	global_load_lds_dwordx4 v[152:153], off
	s_mov_b32 m0, s4
	s_mov_b64 s[4:5], 0x2fc00
	v_bfe_u32 v154, v156, 2, 3
	v_lshl_add_u64 v[152:153], v[150:151], 0, s[4:5]
	v_readlane_b32 s5, v245, 20
	s_mov_b32 s4, m0
	s_mov_b32 m0, s5
	s_nop 0
	global_load_lds_dwordx4 v[152:153], off
	s_mov_b32 m0, s4
	s_mov_b64 s[4:5], 0x5fc00
	v_or_b32_e32 v149, v149, v154
	v_lshl_add_u64 v[152:153], v[150:151], 0, s[4:5]
	v_readlane_b32 s5, v245, 21
	s_mov_b32 s4, m0
	s_mov_b32 m0, s5
	s_nop 0
	global_load_lds_dwordx4 v[152:153], off
	s_mov_b32 m0, s4
	s_mov_b64 s[4:5], 0x8fc00
	v_mul_lo_u32 v149, v149, s88
	v_lshl_add_u64 v[152:153], v[150:151], 0, s[4:5]
	v_readlane_b32 s5, v245, 23
	s_mov_b32 s4, m0
	s_mov_b32 m0, s5
	s_nop 0
	global_load_lds_dwordx4 v[152:153], off
	s_mov_b32 m0, s4
	v_add_lshl_u32 v170, v155, v149, 1
	s_mov_b32 s4, m0
	s_mov_b32 m0, s64
	s_nop 0
	global_load_lds_dwordx4 v[150:151], off
	s_mov_b32 m0, s4
	v_mov_b32_e32 v171, v1
	v_lshl_add_u64 v[150:151], s[80:81], 0, v[170:171]
	v_readlane_b32 s5, v245, 24
	s_mov_b32 s4, m0
	s_mov_b32 m0, s5
	s_nop 0
	global_load_lds_dwordx4 v[150:151], off
	s_mov_b32 m0, s4
	v_lshlrev_b32_e32 v150, 2, v156
	v_readlane_b32 s4, v245, 25
	v_and_b32_e32 v155, 4, v150
	v_bitop3_b32 v150, v150, v154, 4 bitop3:0x6c
	v_lshl_add_u32 v149, v156, 6, s4
	v_and_b32_e32 v149, 0xffffff80, v149
	v_add_u32_e32 v149, s63, v149
	v_lshl_add_u32 v150, v150, 4, v149
	s_ashr_i32 s101, s2, 31
	s_mov_b32 s100, s2
	s_lshl_b64 s[100:101], s[100:101], 2
	s_sub_u32 s100, s7, s100
	s_subb_u32 s101, s33, s101
	v_mov_b32_e32 v248, 0
	global_load_dword v249, v248, s[100:101] offset:28 sc1
	s_add_u32 s100, s80, 0x30000
	s_addc_u32 s101, s81, 0
	v_lshl_add_u64 v[250:251], s[100:101], 0, v[146:147]
	v_lshl_add_u64 v[252:253], s[100:101], 0, v[170:171]
	v_readlane_b32 s98, v245, 27
	s_mov_b32 s99, m0
	s_mov_b32 m0, s98
	s_nop 0
	global_load_lds_dwordx4 v[250:251], off
	v_readlane_b32 s98, v245, 28
	s_nop 0
	s_mov_b32 m0, s98
	s_nop 0
	global_load_lds_dwordx4 v[252:253], off
	s_add_u32 s100, s80, 0x60000
	s_addc_u32 s101, s81, 0
	v_lshl_add_u64 v[250:251], s[100:101], 0, v[146:147]
	v_lshl_add_u64 v[252:253], s[100:101], 0, v[170:171]
	v_readlane_b32 s98, v245, 29
	s_nop 0
	s_mov_b32 m0, s98
	s_nop 0
	global_load_lds_dwordx4 v[250:251], off
	v_readlane_b32 s98, v245, 30
	s_nop 0
	s_mov_b32 m0, s98
	s_nop 0
	global_load_lds_dwordx4 v[252:253], off
	s_mov_b32 m0, s99
	s_mov_b32 s4, s2
	s_mov_b32 s5, s3
	s_ashr_i32 s77, s76, 31
	v_permlane32_swap_b32_e32 v175, v0
	s_nop 0
	v_add_f32_e32 v0, v175, v0
	v_div_scale_f32 v98, s[2:3], v0, v0, 1.0
	v_rcp_f32_e32 v99, v98
	s_nop 0
	v_fma_f32 v100, -v98, v99, 1.0
	v_fmac_f32_e32 v99, v100, v99
	v_div_scale_f32 v100, vcc, 1.0, v0, 1.0
	v_mul_f32_e32 v101, v100, v99
	v_fma_f32 v102, -v98, v101, v100
	v_fmac_f32_e32 v101, v102, v99
	v_fma_f32 v98, -v98, v101, v100
	v_div_fmas_f32 v98, v98, v99, v101
	v_div_fixup_f32 v0, v98, v0, 1.0
	v_mov_b32_e32 v98, v174
	s_nop 1
	v_permlane32_swap_b32_e32 v174, v98
	s_nop 0
	v_add_f32_e32 v98, v174, v98
	v_div_scale_f32 v99, s[2:3], v98, v98, 1.0
	v_rcp_f32_e32 v100, v99
	s_mov_b32 s2, 0xf800000
	v_fma_f32 v101, -v99, v100, 1.0
	v_fmac_f32_e32 v100, v101, v100
	v_div_scale_f32 v101, vcc, 1.0, v98, 1.0
	v_mul_f32_e32 v102, v101, v100
	v_fma_f32 v103, -v99, v102, v101
	v_fmac_f32_e32 v102, v103, v100
	v_fma_f32 v99, -v99, v102, v101
	v_div_fmas_f32 v99, v99, v100, v102
	v_div_fixup_f32 v98, v99, v98, 1.0
	v_mul_f32_e32 v98, v183, v98
	v_mul_f32_e32 v66, v66, v98
	v_fma_f32 v50, v50, v0, -v66
	v_mul_f32_e32 v66, v67, v98
	v_fma_f32 v51, v51, v0, -v66
	v_mul_f32_e32 v66, v51, v51
	v_mul_f32_e32 v67, v68, v98
	v_fmac_f32_e32 v66, v50, v50
	v_fma_f32 v52, v52, v0, -v67
	v_mul_f32_e32 v67, v69, v98
	v_fmac_f32_e32 v66, v52, v52
	v_fma_f32 v53, v53, v0, -v67
	v_mul_f32_e32 v67, v70, v98
	v_fmac_f32_e32 v66, v53, v53
	v_fma_f32 v54, v54, v0, -v67
	v_mul_f32_e32 v67, v71, v98
	v_fmac_f32_e32 v66, v54, v54
	v_fma_f32 v55, v55, v0, -v67
	v_mul_f32_e32 v67, v72, v98
	v_fmac_f32_e32 v66, v55, v55
	v_fma_f32 v56, v56, v0, -v67
	v_mul_f32_e32 v67, v73, v98
	v_fmac_f32_e32 v66, v56, v56
	v_fma_f32 v57, v57, v0, -v67
	v_mul_f32_e32 v67, v74, v98
	v_fmac_f32_e32 v66, v57, v57
	v_fma_f32 v58, v58, v0, -v67
	v_mul_f32_e32 v67, v75, v98
	v_fmac_f32_e32 v66, v58, v58
	v_fma_f32 v59, v59, v0, -v67
	v_mul_f32_e32 v67, v76, v98
	v_fmac_f32_e32 v66, v59, v59
	v_fma_f32 v60, v60, v0, -v67
	v_mul_f32_e32 v67, v77, v98
	v_fmac_f32_e32 v66, v60, v60
	v_fma_f32 v61, v61, v0, -v67
	v_mul_f32_e32 v67, v78, v98
	v_fmac_f32_e32 v66, v61, v61
	v_fma_f32 v62, v62, v0, -v67
	v_mul_f32_e32 v67, v79, v98
	v_fmac_f32_e32 v66, v62, v62
	v_fma_f32 v63, v63, v0, -v67
	v_mul_f32_e32 v67, v80, v98
	v_fmac_f32_e32 v66, v63, v63
	v_fma_f32 v64, v64, v0, -v67
	v_mul_f32_e32 v67, v81, v98
	v_fmac_f32_e32 v66, v64, v64
	v_fma_f32 v65, v65, v0, -v67
	v_mul_f32_e32 v34, v34, v98
	v_fmac_f32_e32 v66, v65, v65
	v_fma_f32 v34, v18, v0, -v34
	v_mul_f32_e32 v18, v35, v98
	v_fmac_f32_e32 v66, v34, v34
	v_fma_f32 v35, v19, v0, -v18
	v_mul_f32_e32 v18, v36, v98
	v_fmac_f32_e32 v66, v35, v35
	v_fma_f32 v36, v20, v0, -v18
	v_mul_f32_e32 v18, v37, v98
	v_fmac_f32_e32 v66, v36, v36
	v_fma_f32 v37, v21, v0, -v18
	v_mul_f32_e32 v18, v38, v98
	v_fmac_f32_e32 v66, v37, v37
	v_fma_f32 v38, v22, v0, -v18
	v_mul_f32_e32 v18, v39, v98
	v_fmac_f32_e32 v66, v38, v38
	v_fma_f32 v39, v23, v0, -v18
	v_mul_f32_e32 v18, v40, v98
	v_fmac_f32_e32 v66, v39, v39
	v_fma_f32 v24, v24, v0, -v18
	v_mul_f32_e32 v18, v41, v98
	v_fmac_f32_e32 v66, v24, v24
	v_fma_f32 v25, v25, v0, -v18
	v_mul_f32_e32 v18, v42, v98
	v_fmac_f32_e32 v66, v25, v25
	v_fma_f32 v26, v26, v0, -v18
	v_mul_f32_e32 v18, v43, v98
	v_fmac_f32_e32 v66, v26, v26
	v_fma_f32 v27, v27, v0, -v18
	v_mul_f32_e32 v18, v44, v98
	v_fmac_f32_e32 v66, v27, v27
	v_fma_f32 v28, v28, v0, -v18
	v_mul_f32_e32 v18, v45, v98
	v_fmac_f32_e32 v66, v28, v28
	v_fma_f32 v29, v29, v0, -v18
	v_mul_f32_e32 v18, v46, v98
	v_fmac_f32_e32 v66, v29, v29
	v_fma_f32 v30, v30, v0, -v18
	v_mul_f32_e32 v18, v47, v98
	v_fmac_f32_e32 v66, v30, v30
	v_fma_f32 v31, v31, v0, -v18
	v_mul_f32_e32 v18, v48, v98
	v_fmac_f32_e32 v66, v31, v31
	v_fma_f32 v32, v32, v0, -v18
	v_mul_f32_e32 v18, v49, v98
	v_fmac_f32_e32 v66, v32, v32
	v_fma_f32 v33, v33, v0, -v18
	v_fmac_f32_e32 v66, v33, v33
	v_mov_b32_e32 v0, v66
	s_nop 1
	v_permlane32_swap_b32_e32 v66, v0
	s_nop 0
	v_add_f32_e32 v0, v66, v0
	v_fmamk_f32 v0, v0, 0x3c800000, v233
	v_cmp_gt_f32_e32 vcc, s2, v0
	v_mul_f32_e32 v18, 0x4f800000, v0
	s_nop 0
	v_cndmask_b32_e32 v0, v0, v18, vcc
	v_sqrt_f32_e32 v18, v0
	s_nop 0
	v_add_u32_e32 v19, -1, v18
	v_fma_f32 v20, -v19, v18, v0
	v_cmp_ge_f32_e64 s[2:3], 0, v20
	v_add_u32_e32 v20, 1, v18
	s_nop 0
	v_cndmask_b32_e64 v19, v18, v19, s[2:3]
	v_fma_f32 v18, -v20, v18, v0
	v_cmp_lt_f32_e64 s[2:3], 0, v18
	s_nop 1
	v_cndmask_b32_e64 v18, v19, v20, s[2:3]
	v_mul_f32_e32 v19, 0x37800000, v18
	v_cndmask_b32_e32 v18, v18, v19, vcc
	v_cmp_class_f32_e32 vcc, v0, v232
	s_nop 1
	v_cndmask_b32_e32 v0, v18, v0, vcc
	v_div_scale_f32 v18, s[2:3], v0, v0, v177
	v_rcp_f32_e32 v19, v18
	v_readlane_b32 s2, v244, 1
	s_add_i32 s2, s2, s68
	v_fma_f32 v20, -v18, v19, 1.0
	v_fmac_f32_e32 v19, v20, v19
	v_div_scale_f32 v20, vcc, v177, v0, v177
	v_mul_f32_e32 v21, v20, v19
	v_fma_f32 v22, -v18, v21, v20
	v_fmac_f32_e32 v21, v22, v19
	v_fma_f32 v18, -v18, v21, v20
	v_div_fmas_f32 v18, v18, v19, v21
	v_div_fixup_f32 v40, v18, v0, v177
	v_or_b32_e32 v0, s2, v185
	v_lshlrev_b64 v[18:19], 11, v[0:1]
	v_lshl_add_u64 v[18:19], s[74:75], 0, v[18:19]
	v_lshl_add_u64 v[18:19], s[76:77], 1, v[18:19]
	v_mul_f32_e32 v0, v50, v40
	v_mul_f32_e32 v20, v51, v40
	v_lshl_add_u64 v[18:19], v[172:173], 1, v[18:19]
	s_mov_b64 s[2:3], 0xb200000
	s_waitcnt vmcnt(18)
	v_mul_f32_e32 v0, v94, v0
	v_mul_f32_e32 v20, v95, v20
	v_lshl_add_u64 v[22:23], v[18:19], 0, s[2:3]
	s_mov_b32 s2, 0xb200000
	v_cvt_pk_bf16_f32 v20, v0, v20
	v_mul_f32_e32 v0, v52, v40
	v_mul_f32_e32 v21, v53, v40
	v_add_co_u32_e32 v18, vcc, s2, v18
	v_mul_f32_e32 v0, v96, v0
	v_mul_f32_e32 v21, v97, v21
	v_addc_co_u32_e32 v19, vcc, 0, v19, vcc
	v_cvt_pk_bf16_f32 v21, v0, v21
	global_store_dwordx2 v[18:19], v[20:21], off
	v_mul_f32_e32 v0, v54, v40
	v_mul_f32_e32 v18, v55, v40
	s_waitcnt vmcnt(18)
	v_mul_f32_e32 v0, v90, v0
	v_mul_f32_e32 v18, v91, v18
	v_cvt_pk_bf16_f32 v18, v0, v18
	v_mul_f32_e32 v0, v56, v40
	v_mul_f32_e32 v19, v57, v40
	v_mul_f32_e32 v0, v92, v0
	v_mul_f32_e32 v19, v93, v19
	v_cvt_pk_bf16_f32 v19, v0, v19
	global_store_dwordx2 v[22:23], v[18:19], off offset:16
	v_mul_f32_e32 v0, v58, v40
	v_mul_f32_e32 v18, v59, v40
	s_waitcnt vmcnt(18)
	v_mul_f32_e32 v0, v86, v0
	v_mul_f32_e32 v18, v87, v18
	v_cvt_pk_bf16_f32 v18, v0, v18
	v_mul_f32_e32 v0, v60, v40
	v_mul_f32_e32 v19, v61, v40
	v_mul_f32_e32 v0, v88, v0
	v_mul_f32_e32 v19, v89, v19
	v_cvt_pk_bf16_f32 v19, v0, v19
	global_store_dwordx2 v[22:23], v[18:19], off offset:32
	v_mul_f32_e32 v0, v62, v40
	v_mul_f32_e32 v18, v63, v40
	s_waitcnt vmcnt(18)
	v_mul_f32_e32 v0, v82, v0
	v_mul_f32_e32 v18, v83, v18
	v_cvt_pk_bf16_f32 v18, v0, v18
	v_mul_f32_e32 v0, v64, v40
	v_mul_f32_e32 v19, v65, v40
	v_mul_f32_e32 v0, v84, v0
	v_mul_f32_e32 v19, v85, v19
	v_cvt_pk_bf16_f32 v19, v0, v19
	v_mul_f32_e32 v0, v34, v40
	s_waitcnt vmcnt(17)
	v_mul_f32_e32 v0, v14, v0
	v_mul_f32_e32 v14, v35, v40
	v_mul_f32_e32 v14, v15, v14
	global_store_dwordx2 v[22:23], v[18:19], off offset:48
	v_cvt_pk_bf16_f32 v14, v0, v14
	v_mul_f32_e32 v0, v36, v40
	v_mul_f32_e32 v15, v37, v40
	v_mul_f32_e32 v0, v16, v0
	v_mul_f32_e32 v15, v17, v15
	v_cvt_pk_bf16_f32 v15, v0, v15
	v_mul_f32_e32 v0, v38, v40
	s_waitcnt vmcnt(17)
	v_mul_f32_e32 v0, v10, v0
	v_mul_f32_e32 v10, v39, v40
	v_mul_f32_e32 v10, v11, v10
	global_store_dwordx2 v[22:23], v[14:15], off offset:64
	v_cvt_pk_bf16_f32 v10, v0, v10
	v_mul_f32_e32 v0, v24, v40
	v_mul_f32_e32 v11, v25, v40
	v_mul_f32_e32 v0, v12, v0
	v_mul_f32_e32 v11, v13, v11
	v_cvt_pk_bf16_f32 v11, v0, v11
	v_mul_f32_e32 v0, v26, v40
	s_waitcnt vmcnt(17)
	v_mul_f32_e32 v0, v6, v0
	v_mul_f32_e32 v6, v27, v40
	v_mul_f32_e32 v6, v7, v6
	global_store_dwordx2 v[22:23], v[10:11], off offset:80
	v_cvt_pk_bf16_f32 v6, v0, v6
	v_mul_f32_e32 v0, v28, v40
	v_mul_f32_e32 v7, v29, v40
	v_mul_f32_e32 v0, v8, v0
	v_mul_f32_e32 v7, v9, v7
	v_cvt_pk_bf16_f32 v7, v0, v7
	v_mul_f32_e32 v0, v30, v40
	s_waitcnt vmcnt(17)
	v_mul_f32_e32 v0, v2, v0
	v_mul_f32_e32 v2, v31, v40
	v_mul_f32_e32 v2, v3, v2
	v_mul_f32_e32 v3, v33, v40
	global_store_dwordx2 v[22:23], v[6:7], off offset:96
	v_cvt_pk_bf16_f32 v2, v0, v2
	v_mul_f32_e32 v0, v32, v40
	v_mul_f32_e32 v3, v5, v3
	v_mul_f32_e32 v0, v4, v0
	v_cvt_pk_bf16_f32 v3, v0, v3
	global_store_dwordx2 v[22:23], v[2:3], off offset:112
	s_mov_b32 s2, s4
	s_mov_b32 s3, s5
	s_mov_b32 s76, s55
	v_mov_b32_e32 v0, v146
	v_mov_b32_e32 v2, v148
	v_mov_b32_e32 v3, v149
	v_mov_b32_e32 v4, v150
	v_mov_b32_e32 v8, v154
	v_mov_b32_e32 v9, v155
	v_mov_b32_e32 v19, v156
	v_mov_b32_e32 v20, v157
	s_mov_b32 s101, 1
	s_waitcnt vmcnt(12)
	s_branch .Lpipe_part2
